# merge GEMM epilogue: 178 canonicalising v_max x,x in front of the 1e-20 gate floors removed (they only matter for signalling NaNs, which bf16 gate values cannot carry)
# baseline (speedup 1.0000x reference)
.Lmg_skip_0:
	v_lshlrev_b32_e32 v186, 16, v160
	v_and_b32_e32 v160, 0xffff0000, v160
	v_lshlrev_b32_e32 v187, 16, v161
	v_and_b32_e32 v161, 0xffff0000, v161
	v_lshlrev_b32_e32 v191, 16, v162
	v_and_b32_e32 v162, 0xffff0000, v162
	v_lshlrev_b32_e32 v195, 16, v163
	v_and_b32_e32 v163, 0xffff0000, v163
	v_max_f32_e32 v199, v186, v186
	v_max_f32_e32 v202, v187, v187
	v_lshlrev_b64 v[186:187], 11, v[182:183]
	s_mov_b64 s[6:7], -1
	s_and_b64 vcc, exec, s[42:43]
	v_max_f32_e32 v200, 0x1e3ce508, v199
	v_max_f32_e32 v201, 0x1e3ce508, v160
	v_max_f32_e32 v202, 0x1e3ce508, v202
	v_max_f32_e32 v203, 0x1e3ce508, v161
	v_max_f32_e32 v160, 0x1e3ce508, v191
	v_max_f32_e32 v161, 0x1e3ce508, v162
	v_max_f32_e32 v162, 0x1e3ce508, v195
	v_max_f32_e32 v163, 0x1e3ce508, v163
	v_lshl_add_u64 v[186:187], s[14:15], 0, v[186:187]
	s_cbranch_vccz .LBB0_60
	v_pk_mul_f32 v[208:209], v[128:129], v[200:201]
	s_mov_b64 s[6:7], 0
	v_cvt_pk_bf16_f32 v234, v208, v209
	v_pk_mul_f32 v[208:209], v[130:131], v[202:203]
	s_nop 0
	v_cvt_pk_bf16_f32 v235, v208, v209
	v_pk_mul_f32 v[208:209], v[124:125], v[160:161]
	s_nop 0
	v_cvt_pk_bf16_f32 v236, v208, v209
	v_pk_mul_f32 v[208:209], v[126:127], v[162:163]
	s_nop 0
	v_cvt_pk_bf16_f32 v237, v208, v209
	v_lshl_add_u64 v[208:209], v[180:181], 1, v[186:187]
	global_store_dwordx4 v[208:209], v[234:237], off
.LBB0_60:
	s_andn2_b64 vcc, exec, s[6:7]
	s_cbranch_vccnz .LBB0_62
	v_lshlrev_b32_e32 v183, 16, v156
	v_lshlrev_b32_e32 v195, 16, v157
	v_and_b32_e32 v191, 0xffff0000, v156
	v_and_b32_e32 v199, 0xffff0000, v157
	v_lshlrev_b32_e32 v157, 16, v158
	v_max_f32_e32 v156, v183, v183
	v_and_b32_e32 v208, 0xffff0000, v158
	v_lshlrev_b32_e32 v209, 16, v159
	v_max_f32_e32 v183, 0x1e3ce508, v195
	v_and_b32_e32 v233, 0xffff0000, v159
	v_max_f32_e32 v157, 0x1e3ce508, v157
	v_max_f32_e32 v159, v208, v208
	v_rcp_f32_e32 v208, v183
	v_rcp_f32_e32 v158, v157
	v_max_f32_e32 v183, 0x1e3ce508, v209
	v_max_f32_e32 v156, 0x1e3ce508, v156
	v_max_f32_e32 v157, 0x1e3ce508, v191
	v_rcp_f32_e32 v234, v183
	v_rcp_f32_e32 v156, v156
	v_rcp_f32_e32 v157, v157
	v_max_f32_e32 v159, 0x1e3ce508, v159
	v_max_f32_e32 v191, 0x1e3ce508, v199
	v_max_f32_e32 v183, 0x1e3ce508, v233
	v_rcp_f32_e32 v159, v159
	v_rcp_f32_e32 v209, v191
	v_rcp_f32_e32 v235, v183
	v_pk_mul_f32 v[156:157], v[200:201], v[156:157]
	v_pk_mul_f32 v[200:201], v[202:203], v[208:209]
	v_pk_mul_f32 v[128:129], v[128:129], v[156:157]
	v_pk_mul_f32 v[156:157], v[160:161], v[158:159]
	v_pk_mul_f32 v[158:159], v[162:163], v[234:235]
	v_pk_mul_f32 v[130:131], v[130:131], v[200:201]
	v_pk_mul_f32 v[126:127], v[126:127], v[158:159]
	v_pk_mul_f32 v[124:125], v[124:125], v[156:157]
.LBB0_62:
	v_ashrrev_i32_e32 v191, 31, v190
	v_lshlrev_b32_e32 v156, 16, v152
	v_and_b32_e32 v152, 0xffff0000, v152
	v_lshlrev_b32_e32 v157, 16, v153
	v_and_b32_e32 v153, 0xffff0000, v153
	v_lshlrev_b32_e32 v158, 16, v154
	v_and_b32_e32 v154, 0xffff0000, v154
	v_lshlrev_b32_e32 v159, 16, v155
	v_and_b32_e32 v155, 0xffff0000, v155
	v_cndmask_b32_e64 v160, 0, 1, s[42:43]
	v_cmp_ne_u32_e64 s[6:7], 1, v160
	v_max_f32_e32 v162, v157, v157
	v_max_f32_e32 v163, v158, v158
	v_max_f32_e32 v183, v159, v159
	v_lshlrev_b64 v[160:161], 11, v[190:191]
	s_mov_b64 s[44:45], -1
	s_andn2_b64 vcc, exec, s[42:43]
	v_max_f32_e32 v156, 0x1e3ce508, v156
	v_max_f32_e32 v157, 0x1e3ce508, v152
	v_max_f32_e32 v158, 0x1e3ce508, v162
	v_max_f32_e32 v159, 0x1e3ce508, v153
	v_max_f32_e32 v152, 0x1e3ce508, v163
	v_max_f32_e32 v153, 0x1e3ce508, v154
	v_max_f32_e32 v154, 0x1e3ce508, v183
	v_max_f32_e32 v155, 0x1e3ce508, v155
	v_lshl_add_u64 v[190:191], s[14:15], 0, v[160:161]
	s_cbranch_vccnz .LBB0_64
	v_pk_mul_f32 v[160:161], v[120:121], v[156:157]
	v_pk_mul_f32 v[162:163], v[122:123], v[158:159]
	v_cvt_pk_bf16_f32 v160, v160, v161
	v_cvt_pk_bf16_f32 v161, v162, v163
	v_pk_mul_f32 v[162:163], v[116:117], v[152:153]
	v_pk_mul_f32 v[200:201], v[118:119], v[154:155]
	v_cvt_pk_bf16_f32 v162, v162, v163
	v_cvt_pk_bf16_f32 v163, v200, v201
	v_lshl_add_u64 v[200:201], v[180:181], 1, v[190:191]
	s_mov_b64 s[44:45], 0
	global_store_dwordx4 v[200:201], v[160:163], off
.LBB0_64:
	s_andn2_b64 vcc, exec, s[44:45]
	s_cbranch_vccnz .LBB0_66
	v_lshlrev_b32_e32 v162, 16, v149
	v_and_b32_e32 v163, 0xffff0000, v149
	v_lshlrev_b32_e32 v149, 16, v150
	v_lshlrev_b32_e32 v160, 16, v148
	v_and_b32_e32 v161, 0xffff0000, v148
	v_max_f32_e32 v149, 0x1e3ce508, v149
	v_and_b32_e32 v183, 0xffff0000, v150
	v_max_f32_e32 v148, v160, v160
	v_rcp_f32_e32 v150, v149
	v_max_f32_e32 v149, v161, v161
	v_max_f32_e32 v148, 0x1e3ce508, v148
	v_max_f32_e32 v149, 0x1e3ce508, v149
	v_max_f32_e32 v160, 0x1e3ce508, v162
	v_max_f32_e32 v161, 0x1e3ce508, v163
	v_rcp_f32_e32 v148, v148
	v_rcp_f32_e32 v149, v149
	v_rcp_f32_e32 v160, v160
	v_rcp_f32_e32 v161, v161
	v_lshlrev_b32_e32 v195, 16, v151
	v_and_b32_e32 v199, 0xffff0000, v151
	v_pk_mul_f32 v[148:149], v[156:157], v[148:149]
	v_pk_mul_f32 v[156:157], v[158:159], v[160:161]
	v_max_f32_e32 v151, 0x1e3ce508, v183
	v_max_f32_e32 v162, 0x1e3ce508, v195
	v_max_f32_e32 v158, 0x1e3ce508, v199
	v_rcp_f32_e32 v151, v151
	v_rcp_f32_e32 v162, v162
	v_rcp_f32_e32 v163, v158
	v_pk_mul_f32 v[120:121], v[120:121], v[148:149]
	v_pk_mul_f32 v[148:149], v[152:153], v[150:151]
	v_pk_mul_f32 v[122:123], v[122:123], v[156:157]
	v_pk_mul_f32 v[150:151], v[154:155], v[162:163]
	v_pk_mul_f32 v[116:117], v[116:117], v[148:149]
	v_pk_mul_f32 v[118:119], v[118:119], v[150:151]
.LBB0_66:
	v_ashrrev_i32_e32 v195, 31, v194
	v_lshlrev_b32_e32 v148, 16, v144
	v_and_b32_e32 v144, 0xffff0000, v144
	v_lshlrev_b32_e32 v149, 16, v145
	v_and_b32_e32 v145, 0xffff0000, v145
	v_lshlrev_b32_e32 v150, 16, v146
	v_and_b32_e32 v146, 0xffff0000, v146
	v_lshlrev_b32_e32 v151, 16, v147
	v_and_b32_e32 v147, 0xffff0000, v147
	v_max_f32_e32 v154, v149, v149
	v_max_f32_e32 v155, v150, v150
	v_max_f32_e32 v156, v151, v151
	v_lshlrev_b64 v[152:153], 11, v[194:195]
	s_mov_b64 s[42:43], -1
	s_and_b64 vcc, exec, s[6:7]
	v_max_f32_e32 v148, 0x1e3ce508, v148
	v_max_f32_e32 v149, 0x1e3ce508, v144
	v_max_f32_e32 v150, 0x1e3ce508, v154
	v_max_f32_e32 v151, 0x1e3ce508, v145
	v_max_f32_e32 v144, 0x1e3ce508, v155
	v_max_f32_e32 v145, 0x1e3ce508, v146
	v_max_f32_e32 v146, 0x1e3ce508, v156
	v_max_f32_e32 v147, 0x1e3ce508, v147
	v_lshl_add_u64 v[194:195], s[14:15], 0, v[152:153]
	s_cbranch_vccnz .LBB0_68
	v_pk_mul_f32 v[152:153], v[112:113], v[148:149]
	v_pk_mul_f32 v[154:155], v[114:115], v[150:151]
	v_cvt_pk_bf16_f32 v152, v152, v153
	v_cvt_pk_bf16_f32 v153, v154, v155
	v_pk_mul_f32 v[154:155], v[108:109], v[144:145]
	v_pk_mul_f32 v[156:157], v[110:111], v[146:147]
	v_cvt_pk_bf16_f32 v154, v154, v155
	v_cvt_pk_bf16_f32 v155, v156, v157
	v_lshl_add_u64 v[156:157], v[180:181], 1, v[194:195]
	s_mov_b64 s[42:43], 0
	global_store_dwordx4 v[156:157], v[152:155], off
.LBB0_68:
	s_andn2_b64 vcc, exec, s[42:43]
	s_cbranch_vccnz .LBB0_70
	v_lshlrev_b32_e32 v154, 16, v141
	v_and_b32_e32 v155, 0xffff0000, v141
	v_lshlrev_b32_e32 v141, 16, v142
	v_lshlrev_b32_e32 v152, 16, v140
	v_and_b32_e32 v153, 0xffff0000, v140
	v_max_f32_e32 v141, 0x1e3ce508, v141
	v_and_b32_e32 v156, 0xffff0000, v142
	v_max_f32_e32 v140, v152, v152
	v_rcp_f32_e32 v142, v141
	v_max_f32_e32 v141, v153, v153
	v_max_f32_e32 v140, 0x1e3ce508, v140
	v_max_f32_e32 v141, 0x1e3ce508, v141
	v_max_f32_e32 v152, 0x1e3ce508, v154
	v_max_f32_e32 v153, 0x1e3ce508, v155
	v_rcp_f32_e32 v140, v140
	v_rcp_f32_e32 v141, v141
	v_rcp_f32_e32 v152, v152
	v_rcp_f32_e32 v153, v153
	v_lshlrev_b32_e32 v157, 16, v143
	v_and_b32_e32 v158, 0xffff0000, v143
	v_pk_mul_f32 v[140:141], v[148:149], v[140:141]
	v_pk_mul_f32 v[148:149], v[150:151], v[152:153]
	v_max_f32_e32 v143, 0x1e3ce508, v156
	v_max_f32_e32 v154, 0x1e3ce508, v157
	v_max_f32_e32 v150, 0x1e3ce508, v158
	v_rcp_f32_e32 v143, v143
	v_rcp_f32_e32 v154, v154
	v_rcp_f32_e32 v155, v150
	v_pk_mul_f32 v[112:113], v[112:113], v[140:141]
	v_pk_mul_f32 v[140:141], v[144:145], v[142:143]
	v_pk_mul_f32 v[114:115], v[114:115], v[148:149]
	v_pk_mul_f32 v[142:143], v[146:147], v[154:155]
	v_pk_mul_f32 v[108:109], v[108:109], v[140:141]
	v_pk_mul_f32 v[110:111], v[110:111], v[142:143]
.LBB0_70:
	v_ashrrev_i32_e32 v199, 31, v198
	v_lshlrev_b32_e32 v140, 16, v136
	v_and_b32_e32 v136, 0xffff0000, v136
	v_lshlrev_b32_e32 v141, 16, v137
	v_and_b32_e32 v137, 0xffff0000, v137
	v_lshlrev_b32_e32 v142, 16, v138
	v_and_b32_e32 v138, 0xffff0000, v138
	v_lshlrev_b32_e32 v143, 16, v139
	v_and_b32_e32 v139, 0xffff0000, v139
	v_max_f32_e32 v146, v141, v141
	v_max_f32_e32 v147, v142, v142
	v_max_f32_e32 v148, v143, v143
	v_lshlrev_b64 v[144:145], 11, v[198:199]
	s_mov_b64 s[42:43], -1
	s_and_b64 vcc, exec, s[6:7]
	v_max_f32_e32 v140, 0x1e3ce508, v140
	v_max_f32_e32 v141, 0x1e3ce508, v136
	v_max_f32_e32 v142, 0x1e3ce508, v146
	v_max_f32_e32 v143, 0x1e3ce508, v137
	v_max_f32_e32 v136, 0x1e3ce508, v147
	v_max_f32_e32 v137, 0x1e3ce508, v138
	v_max_f32_e32 v138, 0x1e3ce508, v148
	v_max_f32_e32 v139, 0x1e3ce508, v139
	v_lshl_add_u64 v[198:199], s[14:15], 0, v[144:145]
	s_cbranch_vccnz .LBB0_72
	v_pk_mul_f32 v[144:145], v[104:105], v[140:141]
	v_pk_mul_f32 v[146:147], v[106:107], v[142:143]
	v_cvt_pk_bf16_f32 v144, v144, v145
	v_cvt_pk_bf16_f32 v145, v146, v147
	v_pk_mul_f32 v[146:147], v[100:101], v[136:137]
	v_pk_mul_f32 v[148:149], v[102:103], v[138:139]
	v_cvt_pk_bf16_f32 v146, v146, v147
	v_cvt_pk_bf16_f32 v147, v148, v149
	v_lshl_add_u64 v[148:149], v[180:181], 1, v[198:199]
	s_mov_b64 s[42:43], 0
	global_store_dwordx4 v[148:149], v[144:147], off
.LBB0_72:
	s_andn2_b64 vcc, exec, s[42:43]
	s_cbranch_vccnz .LBB0_74
	s_waitcnt vmcnt(0)
	v_lshlrev_b32_e32 v146, 16, v133
	v_and_b32_e32 v147, 0xffff0000, v133
	v_lshlrev_b32_e32 v133, 16, v134
	v_lshlrev_b32_e32 v144, 16, v132
	v_and_b32_e32 v145, 0xffff0000, v132
	v_max_f32_e32 v133, 0x1e3ce508, v133
	v_and_b32_e32 v148, 0xffff0000, v134
	v_max_f32_e32 v132, v144, v144
	v_rcp_f32_e32 v134, v133
	v_max_f32_e32 v133, v145, v145
	v_max_f32_e32 v132, 0x1e3ce508, v132
	v_max_f32_e32 v133, 0x1e3ce508, v133
	v_max_f32_e32 v144, 0x1e3ce508, v146
	v_max_f32_e32 v145, 0x1e3ce508, v147
	v_rcp_f32_e32 v132, v132
	v_rcp_f32_e32 v133, v133
	v_rcp_f32_e32 v144, v144
	v_rcp_f32_e32 v145, v145
	v_lshlrev_b32_e32 v149, 16, v135
	v_and_b32_e32 v150, 0xffff0000, v135
	v_pk_mul_f32 v[132:133], v[140:141], v[132:133]
	v_pk_mul_f32 v[140:141], v[142:143], v[144:145]
	v_max_f32_e32 v135, 0x1e3ce508, v148
	v_max_f32_e32 v146, 0x1e3ce508, v149
	v_max_f32_e32 v142, 0x1e3ce508, v150
	v_rcp_f32_e32 v135, v135
	v_rcp_f32_e32 v146, v146
	v_rcp_f32_e32 v147, v142
	v_pk_mul_f32 v[104:105], v[104:105], v[132:133]
	v_pk_mul_f32 v[132:133], v[136:137], v[134:135]
	v_pk_mul_f32 v[106:107], v[106:107], v[140:141]
	v_pk_mul_f32 v[134:135], v[138:139], v[146:147]
	v_pk_mul_f32 v[100:101], v[100:101], v[132:133]
	v_pk_mul_f32 v[102:103], v[102:103], v[134:135]

.Lmg_skip_1:
	v_lshlrev_b32_e32 v183, 16, v160
	v_and_b32_e32 v160, 0xffff0000, v160
	v_lshlrev_b32_e32 v184, 16, v161
	v_and_b32_e32 v161, 0xffff0000, v161
	v_lshlrev_b32_e32 v185, 16, v162
	v_and_b32_e32 v162, 0xffff0000, v162
	v_lshlrev_b32_e32 v188, 16, v163
	v_and_b32_e32 v163, 0xffff0000, v163
	v_max_f32_e32 v189, v184, v184
	v_max_f32_e32 v192, v185, v185
	v_max_f32_e32 v193, v188, v188
	s_mov_b64 s[42:43], -1
	s_and_b64 vcc, exec, s[6:7]
	v_max_f32_e32 v184, 0x1e3ce508, v183
	v_max_f32_e32 v185, 0x1e3ce508, v160
	v_max_f32_e32 v188, 0x1e3ce508, v189
	v_max_f32_e32 v189, 0x1e3ce508, v161
	v_max_f32_e32 v160, 0x1e3ce508, v192
	v_max_f32_e32 v161, 0x1e3ce508, v162
	v_max_f32_e32 v162, 0x1e3ce508, v193
	v_max_f32_e32 v163, 0x1e3ce508, v163
	s_cbranch_vccnz .LBB0_84
	v_pk_mul_f32 v[192:193], v[96:97], v[184:185]
	v_lshl_add_u64 v[186:187], v[180:181], 1, v[186:187]
	v_cvt_pk_bf16_f32 v200, v192, v193
	v_pk_mul_f32 v[192:193], v[98:99], v[188:189]
	s_mov_b64 s[42:43], 0
	v_cvt_pk_bf16_f32 v201, v192, v193
	v_pk_mul_f32 v[192:193], v[92:93], v[160:161]
	s_nop 0
	v_cvt_pk_bf16_f32 v202, v192, v193
	v_pk_mul_f32 v[192:193], v[94:95], v[162:163]
	s_nop 0
	v_cvt_pk_bf16_f32 v203, v192, v193
	global_store_dwordx4 v[186:187], v[200:203], off offset:256
.LBB0_84:
	s_andn2_b64 vcc, exec, s[42:43]
	s_cbranch_vccnz .LBB0_86
	v_lshlrev_b32_e32 v183, 16, v156
	v_lshlrev_b32_e32 v187, 16, v157
	v_and_b32_e32 v192, 0xffff0000, v157
	v_lshlrev_b32_e32 v157, 16, v158
	v_and_b32_e32 v186, 0xffff0000, v156
	v_max_f32_e32 v156, v183, v183
	v_lshlrev_b32_e32 v196, 16, v159
	v_max_f32_e32 v157, 0x1e3ce508, v157
	v_max_f32_e32 v183, 0x1e3ce508, v187
	v_and_b32_e32 v193, 0xffff0000, v158
	v_rcp_f32_e32 v158, v157
	v_max_f32_e32 v157, v186, v186
	v_rcp_f32_e32 v186, v183
	v_and_b32_e32 v197, 0xffff0000, v159
	v_max_f32_e32 v183, 0x1e3ce508, v196
	v_max_f32_e32 v156, 0x1e3ce508, v156
	v_max_f32_e32 v157, 0x1e3ce508, v157
	v_max_f32_e32 v187, v192, v192
	v_rcp_f32_e32 v192, v183
	v_rcp_f32_e32 v156, v156
	v_rcp_f32_e32 v157, v157
	v_max_f32_e32 v159, 0x1e3ce508, v193
	v_max_f32_e32 v187, 0x1e3ce508, v187
	v_max_f32_e32 v183, 0x1e3ce508, v197
	v_rcp_f32_e32 v159, v159
	v_rcp_f32_e32 v187, v187
	v_rcp_f32_e32 v193, v183
	v_pk_mul_f32 v[156:157], v[184:185], v[156:157]
	v_pk_mul_f32 v[184:185], v[188:189], v[186:187]
	v_pk_mul_f32 v[96:97], v[96:97], v[156:157]
	v_pk_mul_f32 v[156:157], v[160:161], v[158:159]
	v_pk_mul_f32 v[158:159], v[162:163], v[192:193]
	v_pk_mul_f32 v[98:99], v[98:99], v[184:185]
	v_pk_mul_f32 v[94:95], v[94:95], v[158:159]
	v_pk_mul_f32 v[92:93], v[92:93], v[156:157]
.LBB0_86:
	v_lshlrev_b32_e32 v156, 16, v152
	v_and_b32_e32 v152, 0xffff0000, v152
	v_lshlrev_b32_e32 v157, 16, v153
	v_and_b32_e32 v153, 0xffff0000, v153
	v_lshlrev_b32_e32 v158, 16, v154
	v_and_b32_e32 v154, 0xffff0000, v154
	v_lshlrev_b32_e32 v159, 16, v155
	v_and_b32_e32 v155, 0xffff0000, v155
	v_max_f32_e32 v160, v157, v157
	v_max_f32_e32 v161, v158, v158
	v_max_f32_e32 v162, v159, v159
	s_mov_b64 s[42:43], -1
	s_and_b64 vcc, exec, s[6:7]
	v_max_f32_e32 v156, 0x1e3ce508, v156
	v_max_f32_e32 v157, 0x1e3ce508, v152
	v_max_f32_e32 v158, 0x1e3ce508, v160
	v_max_f32_e32 v159, 0x1e3ce508, v153
	v_max_f32_e32 v152, 0x1e3ce508, v161
	v_max_f32_e32 v153, 0x1e3ce508, v154
	v_max_f32_e32 v154, 0x1e3ce508, v162
	v_max_f32_e32 v155, 0x1e3ce508, v155
	s_cbranch_vccnz .LBB0_88
	v_pk_mul_f32 v[160:161], v[88:89], v[156:157]
	v_pk_mul_f32 v[162:163], v[90:91], v[158:159]
	v_cvt_pk_bf16_f32 v160, v160, v161
	v_cvt_pk_bf16_f32 v161, v162, v163
	v_pk_mul_f32 v[162:163], v[84:85], v[152:153]
	v_pk_mul_f32 v[184:185], v[86:87], v[154:155]
	v_cvt_pk_bf16_f32 v162, v162, v163
	v_cvt_pk_bf16_f32 v163, v184, v185
	v_lshl_add_u64 v[184:185], v[180:181], 1, v[190:191]
	s_mov_b64 s[42:43], 0
	global_store_dwordx4 v[184:185], v[160:163], off offset:256
.LBB0_88:
	s_andn2_b64 vcc, exec, s[42:43]
	s_cbranch_vccnz .LBB0_90
	v_lshlrev_b32_e32 v162, 16, v149
	v_and_b32_e32 v163, 0xffff0000, v149
	v_lshlrev_b32_e32 v149, 16, v150
	v_lshlrev_b32_e32 v160, 16, v148
	v_and_b32_e32 v161, 0xffff0000, v148
	v_max_f32_e32 v149, 0x1e3ce508, v149
	v_and_b32_e32 v183, 0xffff0000, v150
	v_max_f32_e32 v148, v160, v160
	v_rcp_f32_e32 v150, v149
	v_max_f32_e32 v149, v161, v161
	v_max_f32_e32 v148, 0x1e3ce508, v148
	v_max_f32_e32 v149, 0x1e3ce508, v149
	v_max_f32_e32 v160, 0x1e3ce508, v162
	v_max_f32_e32 v161, 0x1e3ce508, v163
	v_rcp_f32_e32 v148, v148
	v_rcp_f32_e32 v149, v149
	v_rcp_f32_e32 v160, v160
	v_rcp_f32_e32 v161, v161
	v_lshlrev_b32_e32 v184, 16, v151
	v_and_b32_e32 v185, 0xffff0000, v151
	v_pk_mul_f32 v[148:149], v[156:157], v[148:149]
	v_pk_mul_f32 v[156:157], v[158:159], v[160:161]
	v_max_f32_e32 v151, 0x1e3ce508, v183
	v_max_f32_e32 v162, 0x1e3ce508, v184
	v_max_f32_e32 v158, 0x1e3ce508, v185
	v_rcp_f32_e32 v151, v151
	v_rcp_f32_e32 v162, v162
	v_rcp_f32_e32 v163, v158
	v_pk_mul_f32 v[88:89], v[88:89], v[148:149]
	v_pk_mul_f32 v[148:149], v[152:153], v[150:151]
	v_pk_mul_f32 v[90:91], v[90:91], v[156:157]
	v_pk_mul_f32 v[150:151], v[154:155], v[162:163]
	v_pk_mul_f32 v[84:85], v[84:85], v[148:149]
	v_pk_mul_f32 v[86:87], v[86:87], v[150:151]
.LBB0_90:
	v_lshlrev_b32_e32 v148, 16, v144
	v_and_b32_e32 v144, 0xffff0000, v144
	v_lshlrev_b32_e32 v149, 16, v145
	v_and_b32_e32 v145, 0xffff0000, v145
	v_lshlrev_b32_e32 v150, 16, v146
	v_and_b32_e32 v146, 0xffff0000, v146
	v_lshlrev_b32_e32 v151, 16, v147
	v_and_b32_e32 v147, 0xffff0000, v147
	v_max_f32_e32 v152, v149, v149
	v_max_f32_e32 v153, v150, v150
	v_max_f32_e32 v154, v151, v151
	s_mov_b64 s[42:43], -1
	s_and_b64 vcc, exec, s[6:7]
	v_max_f32_e32 v148, 0x1e3ce508, v148
	v_max_f32_e32 v149, 0x1e3ce508, v144
	v_max_f32_e32 v150, 0x1e3ce508, v152
	v_max_f32_e32 v151, 0x1e3ce508, v145
	v_max_f32_e32 v144, 0x1e3ce508, v153
	v_max_f32_e32 v145, 0x1e3ce508, v146
	v_max_f32_e32 v146, 0x1e3ce508, v154
	v_max_f32_e32 v147, 0x1e3ce508, v147
	s_cbranch_vccnz .LBB0_92
	v_pk_mul_f32 v[152:153], v[80:81], v[148:149]
	v_pk_mul_f32 v[154:155], v[82:83], v[150:151]
	v_cvt_pk_bf16_f32 v152, v152, v153
	v_cvt_pk_bf16_f32 v153, v154, v155
	v_pk_mul_f32 v[154:155], v[76:77], v[144:145]
	v_pk_mul_f32 v[156:157], v[78:79], v[146:147]
	v_cvt_pk_bf16_f32 v154, v154, v155
	v_cvt_pk_bf16_f32 v155, v156, v157
	v_lshl_add_u64 v[156:157], v[180:181], 1, v[194:195]
	s_mov_b64 s[42:43], 0
	global_store_dwordx4 v[156:157], v[152:155], off offset:256
.LBB0_92:
	s_andn2_b64 vcc, exec, s[42:43]
	s_cbranch_vccnz .LBB0_94
	v_lshlrev_b32_e32 v154, 16, v141
	v_and_b32_e32 v155, 0xffff0000, v141
	v_lshlrev_b32_e32 v141, 16, v142
	v_lshlrev_b32_e32 v152, 16, v140
	v_and_b32_e32 v153, 0xffff0000, v140
	v_max_f32_e32 v141, 0x1e3ce508, v141
	v_and_b32_e32 v156, 0xffff0000, v142
	v_max_f32_e32 v140, v152, v152
	v_rcp_f32_e32 v142, v141
	v_max_f32_e32 v141, v153, v153
	v_max_f32_e32 v140, 0x1e3ce508, v140
	v_max_f32_e32 v141, 0x1e3ce508, v141
	v_max_f32_e32 v152, 0x1e3ce508, v154
	v_max_f32_e32 v153, 0x1e3ce508, v155
	v_rcp_f32_e32 v140, v140
	v_rcp_f32_e32 v141, v141
	v_rcp_f32_e32 v152, v152
	v_rcp_f32_e32 v153, v153
	v_lshlrev_b32_e32 v157, 16, v143
	v_and_b32_e32 v158, 0xffff0000, v143
	v_pk_mul_f32 v[140:141], v[148:149], v[140:141]
	v_pk_mul_f32 v[148:149], v[150:151], v[152:153]
	v_max_f32_e32 v143, 0x1e3ce508, v156
	v_max_f32_e32 v154, 0x1e3ce508, v157
	v_max_f32_e32 v150, 0x1e3ce508, v158
	v_rcp_f32_e32 v143, v143
	v_rcp_f32_e32 v154, v154
	v_rcp_f32_e32 v155, v150
	v_pk_mul_f32 v[80:81], v[80:81], v[140:141]
	v_pk_mul_f32 v[140:141], v[144:145], v[142:143]
	v_pk_mul_f32 v[82:83], v[82:83], v[148:149]
	v_pk_mul_f32 v[142:143], v[146:147], v[154:155]
	v_pk_mul_f32 v[76:77], v[76:77], v[140:141]
	v_pk_mul_f32 v[78:79], v[78:79], v[142:143]
.LBB0_94:
	v_lshlrev_b32_e32 v140, 16, v136
	v_and_b32_e32 v136, 0xffff0000, v136
	v_lshlrev_b32_e32 v141, 16, v137
	v_and_b32_e32 v137, 0xffff0000, v137
	v_lshlrev_b32_e32 v142, 16, v138
	v_and_b32_e32 v138, 0xffff0000, v138
	v_lshlrev_b32_e32 v143, 16, v139
	v_and_b32_e32 v139, 0xffff0000, v139
	v_max_f32_e32 v144, v141, v141
	v_max_f32_e32 v145, v142, v142
	v_max_f32_e32 v146, v143, v143
	s_mov_b64 s[42:43], -1
	s_and_b64 vcc, exec, s[6:7]
	v_max_f32_e32 v140, 0x1e3ce508, v140
	v_max_f32_e32 v141, 0x1e3ce508, v136
	v_max_f32_e32 v142, 0x1e3ce508, v144
	v_max_f32_e32 v143, 0x1e3ce508, v137
	v_max_f32_e32 v136, 0x1e3ce508, v145
	v_max_f32_e32 v137, 0x1e3ce508, v138
	v_max_f32_e32 v138, 0x1e3ce508, v146
	v_max_f32_e32 v139, 0x1e3ce508, v139
	s_cbranch_vccnz .LBB0_96
	v_pk_mul_f32 v[144:145], v[72:73], v[140:141]
	v_pk_mul_f32 v[146:147], v[74:75], v[142:143]
	v_cvt_pk_bf16_f32 v144, v144, v145
	v_cvt_pk_bf16_f32 v145, v146, v147
	v_pk_mul_f32 v[146:147], v[68:69], v[136:137]
	v_pk_mul_f32 v[148:149], v[70:71], v[138:139]
	v_cvt_pk_bf16_f32 v146, v146, v147
	v_cvt_pk_bf16_f32 v147, v148, v149
	v_lshl_add_u64 v[148:149], v[180:181], 1, v[198:199]
	s_mov_b64 s[42:43], 0
	global_store_dwordx4 v[148:149], v[144:147], off offset:256
.LBB0_96:
	s_andn2_b64 vcc, exec, s[42:43]
	s_cbranch_vccnz .LBB0_98
	s_waitcnt vmcnt(0)
	v_lshlrev_b32_e32 v146, 16, v133
	v_and_b32_e32 v147, 0xffff0000, v133
	v_lshlrev_b32_e32 v133, 16, v134
	v_lshlrev_b32_e32 v144, 16, v132
	v_and_b32_e32 v145, 0xffff0000, v132
	v_max_f32_e32 v133, 0x1e3ce508, v133
	v_and_b32_e32 v148, 0xffff0000, v134
	v_max_f32_e32 v132, v144, v144
	v_rcp_f32_e32 v134, v133
	v_max_f32_e32 v133, v145, v145
	v_max_f32_e32 v132, 0x1e3ce508, v132
	v_max_f32_e32 v133, 0x1e3ce508, v133
	v_max_f32_e32 v144, 0x1e3ce508, v146
	v_max_f32_e32 v145, 0x1e3ce508, v147
	v_rcp_f32_e32 v132, v132
	v_rcp_f32_e32 v133, v133
	v_rcp_f32_e32 v144, v144
	v_rcp_f32_e32 v145, v145
	v_lshlrev_b32_e32 v149, 16, v135
	v_and_b32_e32 v150, 0xffff0000, v135
	v_pk_mul_f32 v[132:133], v[140:141], v[132:133]
	v_pk_mul_f32 v[140:141], v[142:143], v[144:145]
	v_max_f32_e32 v135, 0x1e3ce508, v148
	v_max_f32_e32 v146, 0x1e3ce508, v149
	v_max_f32_e32 v142, 0x1e3ce508, v150
	v_rcp_f32_e32 v135, v135
	v_rcp_f32_e32 v146, v146
	v_rcp_f32_e32 v147, v142
	v_pk_mul_f32 v[72:73], v[72:73], v[132:133]
	v_pk_mul_f32 v[132:133], v[136:137], v[134:135]
	v_pk_mul_f32 v[74:75], v[74:75], v[140:141]
	v_pk_mul_f32 v[134:135], v[138:139], v[146:147]
	v_pk_mul_f32 v[68:69], v[68:69], v[132:133]
	v_pk_mul_f32 v[70:71], v[70:71], v[134:135]

.Lmg_skip_2:
	v_ashrrev_i32_e32 v199, 31, v198
	v_lshlrev_b32_e32 v182, 16, v160
	v_and_b32_e32 v160, 0xffff0000, v160
	v_lshlrev_b32_e32 v183, 16, v161
	v_and_b32_e32 v161, 0xffff0000, v161
	v_lshlrev_b32_e32 v189, 16, v162
	v_and_b32_e32 v162, 0xffff0000, v162
	v_lshlrev_b32_e32 v191, 16, v163
	v_and_b32_e32 v163, 0xffff0000, v163
	v_max_f32_e32 v195, v182, v182
	v_max_f32_e32 v200, v183, v183
	v_lshlrev_b64 v[182:183], 11, v[198:199]
	s_mov_b64 s[40:41], -1
	s_and_b64 vcc, exec, s[6:7]
	v_max_f32_e32 v198, 0x1e3ce508, v195
	v_max_f32_e32 v199, 0x1e3ce508, v160
	v_max_f32_e32 v200, 0x1e3ce508, v200
	v_max_f32_e32 v201, 0x1e3ce508, v161
	v_max_f32_e32 v160, 0x1e3ce508, v189
	v_max_f32_e32 v161, 0x1e3ce508, v162
	v_max_f32_e32 v162, 0x1e3ce508, v191
	v_max_f32_e32 v163, 0x1e3ce508, v163
	v_lshl_add_u64 v[182:183], s[14:15], 0, v[182:183]
	s_cbranch_vccnz .LBB0_108
	v_pk_mul_f32 v[202:203], v[64:65], v[198:199]
	s_mov_b64 s[40:41], 0
	v_cvt_pk_bf16_f32 v234, v202, v203
	v_pk_mul_f32 v[202:203], v[66:67], v[200:201]
	s_nop 0
	v_cvt_pk_bf16_f32 v235, v202, v203
	v_pk_mul_f32 v[202:203], v[60:61], v[160:161]
	s_nop 0
	v_cvt_pk_bf16_f32 v236, v202, v203
	v_pk_mul_f32 v[202:203], v[62:63], v[162:163]
	s_nop 0
	v_cvt_pk_bf16_f32 v237, v202, v203
	v_lshl_add_u64 v[202:203], v[180:181], 1, v[182:183]
	global_store_dwordx4 v[202:203], v[234:237], off
.LBB0_108:
	s_andn2_b64 vcc, exec, s[40:41]
	s_cbranch_vccnz .LBB0_110
	v_lshlrev_b32_e32 v189, 16, v156
	v_lshlrev_b32_e32 v195, 16, v157
	v_and_b32_e32 v191, 0xffff0000, v156
	v_and_b32_e32 v203, 0xffff0000, v157
	v_lshlrev_b32_e32 v157, 16, v158
	v_max_f32_e32 v156, v189, v189
	v_and_b32_e32 v202, 0xffff0000, v158
	v_lshlrev_b32_e32 v208, 16, v159
	v_max_f32_e32 v189, 0x1e3ce508, v195
	v_and_b32_e32 v209, 0xffff0000, v159
	v_max_f32_e32 v157, 0x1e3ce508, v157
	v_max_f32_e32 v159, v202, v202
	v_rcp_f32_e32 v202, v189
	v_rcp_f32_e32 v158, v157
	v_max_f32_e32 v189, 0x1e3ce508, v208
	v_max_f32_e32 v156, 0x1e3ce508, v156
	v_max_f32_e32 v157, 0x1e3ce508, v191
	v_rcp_f32_e32 v208, v189
	v_rcp_f32_e32 v156, v156
	v_rcp_f32_e32 v157, v157
	v_max_f32_e32 v159, 0x1e3ce508, v159
	v_max_f32_e32 v191, 0x1e3ce508, v203
	v_max_f32_e32 v189, 0x1e3ce508, v209
	v_rcp_f32_e32 v159, v159
	v_rcp_f32_e32 v203, v191
	v_rcp_f32_e32 v209, v189
	v_pk_mul_f32 v[156:157], v[198:199], v[156:157]
	v_pk_mul_f32 v[198:199], v[200:201], v[202:203]
	v_pk_mul_f32 v[64:65], v[64:65], v[156:157]
	v_pk_mul_f32 v[156:157], v[160:161], v[158:159]
	v_pk_mul_f32 v[158:159], v[162:163], v[208:209]
	v_pk_mul_f32 v[66:67], v[66:67], v[198:199]
	v_pk_mul_f32 v[62:63], v[62:63], v[158:159]
	v_pk_mul_f32 v[60:61], v[60:61], v[156:157]
.LBB0_110:
	v_ashrrev_i32_e32 v189, 31, v188
	v_lshlrev_b32_e32 v156, 16, v152
	v_and_b32_e32 v152, 0xffff0000, v152
	v_lshlrev_b32_e32 v157, 16, v153
	v_and_b32_e32 v153, 0xffff0000, v153
	v_lshlrev_b32_e32 v158, 16, v154
	v_and_b32_e32 v154, 0xffff0000, v154
	v_lshlrev_b32_e32 v159, 16, v155
	v_and_b32_e32 v155, 0xffff0000, v155
	v_max_f32_e32 v162, v157, v157
	v_max_f32_e32 v163, v158, v158
	v_max_f32_e32 v191, v159, v159
	v_lshlrev_b64 v[160:161], 11, v[188:189]
	s_mov_b64 s[40:41], -1
	s_and_b64 vcc, exec, s[6:7]
	v_max_f32_e32 v156, 0x1e3ce508, v156
	v_max_f32_e32 v157, 0x1e3ce508, v152
	v_max_f32_e32 v158, 0x1e3ce508, v162
	v_max_f32_e32 v159, 0x1e3ce508, v153
	v_max_f32_e32 v152, 0x1e3ce508, v163
	v_max_f32_e32 v153, 0x1e3ce508, v154
	v_max_f32_e32 v154, 0x1e3ce508, v191
	v_max_f32_e32 v155, 0x1e3ce508, v155
	v_lshl_add_u64 v[188:189], s[14:15], 0, v[160:161]
	s_cbranch_vccnz .LBB0_112
	v_pk_mul_f32 v[160:161], v[56:57], v[156:157]
	v_pk_mul_f32 v[162:163], v[58:59], v[158:159]
	v_cvt_pk_bf16_f32 v160, v160, v161
	v_cvt_pk_bf16_f32 v161, v162, v163
	v_pk_mul_f32 v[162:163], v[52:53], v[152:153]
	v_pk_mul_f32 v[198:199], v[54:55], v[154:155]
	v_cvt_pk_bf16_f32 v162, v162, v163
	v_cvt_pk_bf16_f32 v163, v198, v199
	v_lshl_add_u64 v[198:199], v[180:181], 1, v[188:189]
	s_mov_b64 s[40:41], 0
	global_store_dwordx4 v[198:199], v[160:163], off
.LBB0_112:
	s_andn2_b64 vcc, exec, s[40:41]
	s_cbranch_vccnz .LBB0_114
	v_lshlrev_b32_e32 v162, 16, v149
	v_and_b32_e32 v163, 0xffff0000, v149
	v_lshlrev_b32_e32 v149, 16, v150
	v_lshlrev_b32_e32 v160, 16, v148
	v_and_b32_e32 v161, 0xffff0000, v148
	v_max_f32_e32 v149, 0x1e3ce508, v149
	v_and_b32_e32 v191, 0xffff0000, v150
	v_max_f32_e32 v148, v160, v160
	v_rcp_f32_e32 v150, v149
	v_max_f32_e32 v149, v161, v161
	v_max_f32_e32 v148, 0x1e3ce508, v148
	v_max_f32_e32 v149, 0x1e3ce508, v149
	v_max_f32_e32 v160, 0x1e3ce508, v162
	v_max_f32_e32 v161, 0x1e3ce508, v163
	v_rcp_f32_e32 v148, v148
	v_rcp_f32_e32 v149, v149
	v_rcp_f32_e32 v160, v160
	v_rcp_f32_e32 v161, v161
	v_lshlrev_b32_e32 v195, 16, v151
	v_and_b32_e32 v198, 0xffff0000, v151
	v_pk_mul_f32 v[148:149], v[156:157], v[148:149]
	v_pk_mul_f32 v[156:157], v[158:159], v[160:161]
	v_max_f32_e32 v151, 0x1e3ce508, v191
	v_max_f32_e32 v162, 0x1e3ce508, v195
	v_max_f32_e32 v158, 0x1e3ce508, v198
	v_rcp_f32_e32 v151, v151
	v_rcp_f32_e32 v162, v162
	v_rcp_f32_e32 v163, v158
	v_pk_mul_f32 v[56:57], v[56:57], v[148:149]
	v_pk_mul_f32 v[148:149], v[152:153], v[150:151]
	v_pk_mul_f32 v[58:59], v[58:59], v[156:157]
	v_pk_mul_f32 v[150:151], v[154:155], v[162:163]
	v_pk_mul_f32 v[52:53], v[52:53], v[148:149]
	v_pk_mul_f32 v[54:55], v[54:55], v[150:151]
.LBB0_114:
	v_ashrrev_i32_e32 v191, 31, v190
	v_lshlrev_b32_e32 v148, 16, v144
	v_and_b32_e32 v144, 0xffff0000, v144
	v_lshlrev_b32_e32 v149, 16, v145
	v_and_b32_e32 v145, 0xffff0000, v145
	v_lshlrev_b32_e32 v150, 16, v146
	v_and_b32_e32 v146, 0xffff0000, v146
	v_lshlrev_b32_e32 v151, 16, v147
	v_and_b32_e32 v147, 0xffff0000, v147
	v_max_f32_e32 v154, v149, v149
	v_max_f32_e32 v155, v150, v150
	v_max_f32_e32 v156, v151, v151
	v_lshlrev_b64 v[152:153], 11, v[190:191]
	s_mov_b64 s[40:41], -1
	s_and_b64 vcc, exec, s[6:7]
	v_max_f32_e32 v148, 0x1e3ce508, v148
	v_max_f32_e32 v149, 0x1e3ce508, v144
	v_max_f32_e32 v150, 0x1e3ce508, v154
	v_max_f32_e32 v151, 0x1e3ce508, v145
	v_max_f32_e32 v144, 0x1e3ce508, v155
	v_max_f32_e32 v145, 0x1e3ce508, v146
	v_max_f32_e32 v146, 0x1e3ce508, v156
	v_max_f32_e32 v147, 0x1e3ce508, v147
	v_lshl_add_u64 v[190:191], s[14:15], 0, v[152:153]
	s_cbranch_vccnz .LBB0_116
	v_pk_mul_f32 v[152:153], v[48:49], v[148:149]
	v_pk_mul_f32 v[154:155], v[50:51], v[150:151]
	v_cvt_pk_bf16_f32 v152, v152, v153
	v_cvt_pk_bf16_f32 v153, v154, v155
	v_pk_mul_f32 v[154:155], v[44:45], v[144:145]
	v_pk_mul_f32 v[156:157], v[46:47], v[146:147]
	v_cvt_pk_bf16_f32 v154, v154, v155
	v_cvt_pk_bf16_f32 v155, v156, v157
	v_lshl_add_u64 v[156:157], v[180:181], 1, v[190:191]
	s_mov_b64 s[40:41], 0
	global_store_dwordx4 v[156:157], v[152:155], off
.LBB0_116:
	s_andn2_b64 vcc, exec, s[40:41]
	s_cbranch_vccnz .LBB0_118
	v_lshlrev_b32_e32 v154, 16, v141
	v_and_b32_e32 v155, 0xffff0000, v141
	v_lshlrev_b32_e32 v141, 16, v142
	v_lshlrev_b32_e32 v152, 16, v140
	v_and_b32_e32 v153, 0xffff0000, v140
	v_max_f32_e32 v141, 0x1e3ce508, v141
	v_and_b32_e32 v156, 0xffff0000, v142
	v_max_f32_e32 v140, v152, v152
	v_rcp_f32_e32 v142, v141
	v_max_f32_e32 v141, v153, v153
	v_max_f32_e32 v140, 0x1e3ce508, v140
	v_max_f32_e32 v141, 0x1e3ce508, v141
	v_max_f32_e32 v152, 0x1e3ce508, v154
	v_max_f32_e32 v153, 0x1e3ce508, v155
	v_rcp_f32_e32 v140, v140
	v_rcp_f32_e32 v141, v141
	v_rcp_f32_e32 v152, v152
	v_rcp_f32_e32 v153, v153
	v_lshlrev_b32_e32 v157, 16, v143
	v_and_b32_e32 v158, 0xffff0000, v143
	v_pk_mul_f32 v[140:141], v[148:149], v[140:141]
	v_pk_mul_f32 v[148:149], v[150:151], v[152:153]
	v_max_f32_e32 v143, 0x1e3ce508, v156
	v_max_f32_e32 v154, 0x1e3ce508, v157
	v_max_f32_e32 v150, 0x1e3ce508, v158
	v_rcp_f32_e32 v143, v143
	v_rcp_f32_e32 v154, v154
	v_rcp_f32_e32 v155, v150
	v_pk_mul_f32 v[48:49], v[48:49], v[140:141]
	v_pk_mul_f32 v[140:141], v[144:145], v[142:143]
	v_pk_mul_f32 v[50:51], v[50:51], v[148:149]
	v_pk_mul_f32 v[142:143], v[146:147], v[154:155]
	v_pk_mul_f32 v[44:45], v[44:45], v[140:141]
	v_pk_mul_f32 v[46:47], v[46:47], v[142:143]
.LBB0_118:
	v_ashrrev_i32_e32 v195, 31, v194
	v_lshlrev_b32_e32 v140, 16, v136
	v_and_b32_e32 v136, 0xffff0000, v136
	v_lshlrev_b32_e32 v141, 16, v137
	v_and_b32_e32 v137, 0xffff0000, v137
	v_lshlrev_b32_e32 v142, 16, v138
	v_and_b32_e32 v138, 0xffff0000, v138
	v_lshlrev_b32_e32 v143, 16, v139
	v_and_b32_e32 v139, 0xffff0000, v139
	v_max_f32_e32 v146, v141, v141
	v_max_f32_e32 v147, v142, v142
	v_max_f32_e32 v148, v143, v143
	v_lshlrev_b64 v[144:145], 11, v[194:195]
	s_mov_b64 s[40:41], -1
	s_and_b64 vcc, exec, s[6:7]
	v_max_f32_e32 v140, 0x1e3ce508, v140
	v_max_f32_e32 v141, 0x1e3ce508, v136
	v_max_f32_e32 v142, 0x1e3ce508, v146
	v_max_f32_e32 v143, 0x1e3ce508, v137
	v_max_f32_e32 v136, 0x1e3ce508, v147
	v_max_f32_e32 v137, 0x1e3ce508, v138
	v_max_f32_e32 v138, 0x1e3ce508, v148
	v_max_f32_e32 v139, 0x1e3ce508, v139
	v_lshl_add_u64 v[194:195], s[14:15], 0, v[144:145]
	s_cbranch_vccnz .LBB0_120
	v_pk_mul_f32 v[144:145], v[40:41], v[140:141]
	v_pk_mul_f32 v[146:147], v[42:43], v[142:143]
	v_cvt_pk_bf16_f32 v144, v144, v145
	v_cvt_pk_bf16_f32 v145, v146, v147
	v_pk_mul_f32 v[146:147], v[36:37], v[136:137]
	v_pk_mul_f32 v[148:149], v[38:39], v[138:139]
	v_cvt_pk_bf16_f32 v146, v146, v147
	v_cvt_pk_bf16_f32 v147, v148, v149
	v_lshl_add_u64 v[148:149], v[180:181], 1, v[194:195]
	s_mov_b64 s[40:41], 0
	global_store_dwordx4 v[148:149], v[144:147], off
.LBB0_120:
	s_andn2_b64 vcc, exec, s[40:41]
	s_cbranch_vccnz .LBB0_122
	s_waitcnt vmcnt(0)
	v_lshlrev_b32_e32 v146, 16, v133
	v_and_b32_e32 v147, 0xffff0000, v133
	v_lshlrev_b32_e32 v133, 16, v134
	v_lshlrev_b32_e32 v144, 16, v132
	v_and_b32_e32 v145, 0xffff0000, v132
	v_max_f32_e32 v133, 0x1e3ce508, v133
	v_and_b32_e32 v148, 0xffff0000, v134
	v_max_f32_e32 v132, v144, v144
	v_rcp_f32_e32 v134, v133
	v_max_f32_e32 v133, v145, v145
	v_max_f32_e32 v132, 0x1e3ce508, v132
	v_max_f32_e32 v133, 0x1e3ce508, v133
	v_max_f32_e32 v144, 0x1e3ce508, v146
	v_max_f32_e32 v145, 0x1e3ce508, v147
	v_rcp_f32_e32 v132, v132
	v_rcp_f32_e32 v133, v133
	v_rcp_f32_e32 v144, v144
	v_rcp_f32_e32 v145, v145
	v_lshlrev_b32_e32 v149, 16, v135
	v_and_b32_e32 v150, 0xffff0000, v135
	v_pk_mul_f32 v[132:133], v[140:141], v[132:133]
	v_pk_mul_f32 v[140:141], v[142:143], v[144:145]
	v_max_f32_e32 v135, 0x1e3ce508, v148
	v_max_f32_e32 v146, 0x1e3ce508, v149
	v_max_f32_e32 v142, 0x1e3ce508, v150
	v_rcp_f32_e32 v135, v135
	v_rcp_f32_e32 v146, v146
	v_rcp_f32_e32 v147, v142
	v_pk_mul_f32 v[40:41], v[40:41], v[132:133]
	v_pk_mul_f32 v[132:133], v[136:137], v[134:135]
	v_pk_mul_f32 v[42:43], v[42:43], v[140:141]
	v_pk_mul_f32 v[134:135], v[138:139], v[146:147]
	v_pk_mul_f32 v[36:37], v[36:37], v[132:133]
	v_pk_mul_f32 v[38:39], v[38:39], v[134:135]

.Lmg_skip_3:
	v_lshlrev_b32_e32 v184, 16, v160
	v_and_b32_e32 v160, 0xffff0000, v160
	v_lshlrev_b32_e32 v185, 16, v161
	v_and_b32_e32 v161, 0xffff0000, v161
	v_lshlrev_b32_e32 v186, 16, v162
	v_and_b32_e32 v162, 0xffff0000, v162
	v_lshlrev_b32_e32 v187, 16, v163
	v_and_b32_e32 v163, 0xffff0000, v163
	v_max_f32_e32 v192, v185, v185
	v_max_f32_e32 v193, v186, v186
	v_max_f32_e32 v196, v187, v187
	s_mov_b64 s[8:9], -1
	s_and_b64 vcc, exec, s[6:7]
	v_max_f32_e32 v184, 0x1e3ce508, v184
	v_max_f32_e32 v185, 0x1e3ce508, v160
	v_max_f32_e32 v186, 0x1e3ce508, v192
	v_max_f32_e32 v187, 0x1e3ce508, v161
	v_max_f32_e32 v160, 0x1e3ce508, v193
	v_max_f32_e32 v161, 0x1e3ce508, v162
	v_max_f32_e32 v162, 0x1e3ce508, v196
	v_max_f32_e32 v163, 0x1e3ce508, v163
	s_cbranch_vccnz .LBB0_132
	v_pk_mul_f32 v[192:193], v[32:33], v[184:185]
	v_lshl_add_u64 v[182:183], v[180:181], 1, v[182:183]
	v_cvt_pk_bf16_f32 v196, v192, v193
	v_pk_mul_f32 v[192:193], v[34:35], v[186:187]
	s_mov_b64 s[8:9], 0
	v_cvt_pk_bf16_f32 v197, v192, v193
	v_pk_mul_f32 v[192:193], v[28:29], v[160:161]
	s_nop 0
	v_cvt_pk_bf16_f32 v198, v192, v193
	v_pk_mul_f32 v[192:193], v[30:31], v[162:163]
	s_nop 0
	v_cvt_pk_bf16_f32 v199, v192, v193
	global_store_dwordx4 v[182:183], v[196:199], off offset:256
.LBB0_132:
	s_andn2_b64 vcc, exec, s[8:9]
	s_cbranch_vccnz .LBB0_134
	v_lshlrev_b32_e32 v192, 16, v157
	v_and_b32_e32 v193, 0xffff0000, v157
	v_lshlrev_b32_e32 v157, 16, v158
	v_lshlrev_b32_e32 v182, 16, v156
	v_and_b32_e32 v183, 0xffff0000, v156
	v_max_f32_e32 v157, 0x1e3ce508, v157
	v_and_b32_e32 v196, 0xffff0000, v158
	v_rcp_f32_e32 v158, v157
	v_max_f32_e32 v156, 0x1e3ce508, v182
	v_max_f32_e32 v157, 0x1e3ce508, v183
	v_rcp_f32_e32 v156, v156
	v_rcp_f32_e32 v157, v157
	v_lshlrev_b32_e32 v197, 16, v159
	v_and_b32_e32 v198, 0xffff0000, v159
	v_max_f32_e32 v182, v192, v192
	v_pk_mul_f32 v[156:157], v[184:185], v[156:157]
	v_max_f32_e32 v159, 0x1e3ce508, v196
	v_max_f32_e32 v182, 0x1e3ce508, v182
	v_max_f32_e32 v183, 0x1e3ce508, v193
	v_max_f32_e32 v192, 0x1e3ce508, v197
	v_max_f32_e32 v184, 0x1e3ce508, v198
	v_rcp_f32_e32 v159, v159
	v_rcp_f32_e32 v182, v182
	v_rcp_f32_e32 v183, v183
	v_rcp_f32_e32 v192, v192
	v_rcp_f32_e32 v193, v184
	v_pk_mul_f32 v[32:33], v[32:33], v[156:157]
	v_pk_mul_f32 v[182:183], v[186:187], v[182:183]
	v_pk_mul_f32 v[156:157], v[160:161], v[158:159]
	v_pk_mul_f32 v[158:159], v[162:163], v[192:193]
	v_pk_mul_f32 v[34:35], v[34:35], v[182:183]
	v_pk_mul_f32 v[30:31], v[30:31], v[158:159]
	v_pk_mul_f32 v[28:29], v[28:29], v[156:157]
.LBB0_134:
	v_lshlrev_b32_e32 v156, 16, v152
	v_and_b32_e32 v152, 0xffff0000, v152
	v_lshlrev_b32_e32 v157, 16, v153
	v_and_b32_e32 v153, 0xffff0000, v153
	v_lshlrev_b32_e32 v158, 16, v154
	v_and_b32_e32 v154, 0xffff0000, v154
	v_lshlrev_b32_e32 v159, 16, v155
	v_and_b32_e32 v155, 0xffff0000, v155
	v_max_f32_e32 v160, v157, v157
	v_max_f32_e32 v161, v158, v158
	v_max_f32_e32 v162, v159, v159
	s_mov_b64 s[8:9], -1
	s_and_b64 vcc, exec, s[6:7]
	v_max_f32_e32 v156, 0x1e3ce508, v156
	v_max_f32_e32 v157, 0x1e3ce508, v152
	v_max_f32_e32 v158, 0x1e3ce508, v160
	v_max_f32_e32 v159, 0x1e3ce508, v153
	v_max_f32_e32 v152, 0x1e3ce508, v161
	v_max_f32_e32 v153, 0x1e3ce508, v154
	v_max_f32_e32 v154, 0x1e3ce508, v162
	v_max_f32_e32 v155, 0x1e3ce508, v155
	s_cbranch_vccnz .LBB0_136
	v_pk_mul_f32 v[160:161], v[24:25], v[156:157]
	v_pk_mul_f32 v[162:163], v[26:27], v[158:159]
	v_cvt_pk_bf16_f32 v160, v160, v161
	v_cvt_pk_bf16_f32 v161, v162, v163
	v_pk_mul_f32 v[162:163], v[20:21], v[152:153]
	v_pk_mul_f32 v[182:183], v[22:23], v[154:155]
	v_cvt_pk_bf16_f32 v162, v162, v163
	v_cvt_pk_bf16_f32 v163, v182, v183
	v_lshl_add_u64 v[182:183], v[180:181], 1, v[188:189]
	s_mov_b64 s[8:9], 0
	global_store_dwordx4 v[182:183], v[160:163], off offset:256
.LBB0_136:
	s_andn2_b64 vcc, exec, s[8:9]
	s_cbranch_vccnz .LBB0_138
	v_lshlrev_b32_e32 v162, 16, v149
	v_and_b32_e32 v163, 0xffff0000, v149
	v_lshlrev_b32_e32 v149, 16, v150
	v_lshlrev_b32_e32 v160, 16, v148
	v_and_b32_e32 v161, 0xffff0000, v148
	v_max_f32_e32 v149, 0x1e3ce508, v149
	v_and_b32_e32 v182, 0xffff0000, v150
	v_max_f32_e32 v148, v160, v160
	v_rcp_f32_e32 v150, v149
	v_max_f32_e32 v149, v161, v161
	v_max_f32_e32 v148, 0x1e3ce508, v148
	v_max_f32_e32 v149, 0x1e3ce508, v149
	v_max_f32_e32 v160, 0x1e3ce508, v162
	v_max_f32_e32 v161, 0x1e3ce508, v163
	v_rcp_f32_e32 v148, v148
	v_rcp_f32_e32 v149, v149
	v_rcp_f32_e32 v160, v160
	v_rcp_f32_e32 v161, v161
	v_lshlrev_b32_e32 v183, 16, v151
	v_and_b32_e32 v184, 0xffff0000, v151
	v_pk_mul_f32 v[148:149], v[156:157], v[148:149]
	v_pk_mul_f32 v[156:157], v[158:159], v[160:161]
	v_max_f32_e32 v151, 0x1e3ce508, v182
	v_max_f32_e32 v162, 0x1e3ce508, v183
	v_max_f32_e32 v158, 0x1e3ce508, v184
	v_rcp_f32_e32 v151, v151
	v_rcp_f32_e32 v162, v162
	v_rcp_f32_e32 v163, v158
	v_pk_mul_f32 v[24:25], v[24:25], v[148:149]
	v_pk_mul_f32 v[148:149], v[152:153], v[150:151]
	v_pk_mul_f32 v[26:27], v[26:27], v[156:157]
	v_pk_mul_f32 v[150:151], v[154:155], v[162:163]
	v_pk_mul_f32 v[20:21], v[20:21], v[148:149]
	v_pk_mul_f32 v[22:23], v[22:23], v[150:151]
.LBB0_138:
	v_lshlrev_b32_e32 v148, 16, v144
	v_and_b32_e32 v144, 0xffff0000, v144
	v_lshlrev_b32_e32 v149, 16, v145
	v_and_b32_e32 v145, 0xffff0000, v145
	v_lshlrev_b32_e32 v150, 16, v146
	v_and_b32_e32 v146, 0xffff0000, v146
	v_lshlrev_b32_e32 v151, 16, v147
	v_and_b32_e32 v147, 0xffff0000, v147
	v_max_f32_e32 v152, v149, v149
	v_max_f32_e32 v153, v150, v150
	v_max_f32_e32 v154, v151, v151
	s_mov_b64 s[8:9], -1
	s_and_b64 vcc, exec, s[6:7]
	v_max_f32_e32 v148, 0x1e3ce508, v148
	v_max_f32_e32 v149, 0x1e3ce508, v144
	v_max_f32_e32 v150, 0x1e3ce508, v152
	v_max_f32_e32 v151, 0x1e3ce508, v145
	v_max_f32_e32 v144, 0x1e3ce508, v153
	v_max_f32_e32 v145, 0x1e3ce508, v146
	v_max_f32_e32 v146, 0x1e3ce508, v154
	v_max_f32_e32 v147, 0x1e3ce508, v147
	s_cbranch_vccnz .LBB0_140
	v_pk_mul_f32 v[152:153], v[16:17], v[148:149]
	v_pk_mul_f32 v[154:155], v[18:19], v[150:151]
	v_cvt_pk_bf16_f32 v152, v152, v153
	v_cvt_pk_bf16_f32 v153, v154, v155
	v_pk_mul_f32 v[154:155], v[12:13], v[144:145]
	v_pk_mul_f32 v[156:157], v[14:15], v[146:147]
	v_cvt_pk_bf16_f32 v154, v154, v155
	v_cvt_pk_bf16_f32 v155, v156, v157
	v_lshl_add_u64 v[156:157], v[180:181], 1, v[190:191]
	s_mov_b64 s[8:9], 0
	global_store_dwordx4 v[156:157], v[152:155], off offset:256
.LBB0_140:
	s_andn2_b64 vcc, exec, s[8:9]
	s_cbranch_vccnz .LBB0_142
	v_lshlrev_b32_e32 v154, 16, v141
	v_and_b32_e32 v155, 0xffff0000, v141
	v_lshlrev_b32_e32 v141, 16, v142
	v_lshlrev_b32_e32 v152, 16, v140
	v_and_b32_e32 v153, 0xffff0000, v140
	v_max_f32_e32 v141, 0x1e3ce508, v141
	v_and_b32_e32 v156, 0xffff0000, v142
	v_max_f32_e32 v140, v152, v152
	v_rcp_f32_e32 v142, v141
	v_max_f32_e32 v141, v153, v153
	v_max_f32_e32 v140, 0x1e3ce508, v140
	v_max_f32_e32 v141, 0x1e3ce508, v141
	v_max_f32_e32 v152, 0x1e3ce508, v154
	v_max_f32_e32 v153, 0x1e3ce508, v155
	v_rcp_f32_e32 v140, v140
	v_rcp_f32_e32 v141, v141
	v_rcp_f32_e32 v152, v152
	v_rcp_f32_e32 v153, v153
	v_lshlrev_b32_e32 v157, 16, v143
	v_and_b32_e32 v158, 0xffff0000, v143
	v_pk_mul_f32 v[140:141], v[148:149], v[140:141]
	v_pk_mul_f32 v[148:149], v[150:151], v[152:153]
	v_max_f32_e32 v143, 0x1e3ce508, v156
	v_max_f32_e32 v154, 0x1e3ce508, v157
	v_max_f32_e32 v150, 0x1e3ce508, v158
	v_rcp_f32_e32 v143, v143
	v_rcp_f32_e32 v154, v154
	v_rcp_f32_e32 v155, v150
	v_pk_mul_f32 v[16:17], v[16:17], v[140:141]
	v_pk_mul_f32 v[140:141], v[144:145], v[142:143]
	v_pk_mul_f32 v[18:19], v[18:19], v[148:149]
	v_pk_mul_f32 v[142:143], v[146:147], v[154:155]
	v_pk_mul_f32 v[12:13], v[12:13], v[140:141]
	v_pk_mul_f32 v[14:15], v[14:15], v[142:143]
.LBB0_142:
	v_lshlrev_b32_e32 v140, 16, v136
	v_and_b32_e32 v136, 0xffff0000, v136
	v_lshlrev_b32_e32 v141, 16, v137
	v_and_b32_e32 v137, 0xffff0000, v137
	v_lshlrev_b32_e32 v142, 16, v138
	v_and_b32_e32 v138, 0xffff0000, v138
	v_lshlrev_b32_e32 v143, 16, v139
	v_and_b32_e32 v139, 0xffff0000, v139
	v_max_f32_e32 v144, v141, v141
	v_max_f32_e32 v145, v142, v142
	v_max_f32_e32 v146, v143, v143
	s_mov_b64 s[8:9], -1
	s_and_b64 vcc, exec, s[6:7]
	v_max_f32_e32 v140, 0x1e3ce508, v140
	v_max_f32_e32 v141, 0x1e3ce508, v136
	v_max_f32_e32 v142, 0x1e3ce508, v144
	v_max_f32_e32 v143, 0x1e3ce508, v137
	v_max_f32_e32 v136, 0x1e3ce508, v145
	v_max_f32_e32 v137, 0x1e3ce508, v138
	v_max_f32_e32 v138, 0x1e3ce508, v146
	v_max_f32_e32 v139, 0x1e3ce508, v139
	s_cbranch_vccnz .LBB0_145
	v_pk_mul_f32 v[144:145], v[8:9], v[140:141]
	v_pk_mul_f32 v[146:147], v[10:11], v[142:143]
	v_cvt_pk_bf16_f32 v144, v144, v145
	v_cvt_pk_bf16_f32 v145, v146, v147
	v_pk_mul_f32 v[146:147], v[4:5], v[136:137]
	v_pk_mul_f32 v[148:149], v[6:7], v[138:139]
	v_cvt_pk_bf16_f32 v146, v146, v147
	v_cvt_pk_bf16_f32 v147, v148, v149
	v_lshl_add_u64 v[148:149], v[180:181], 1, v[194:195]
	global_store_dwordx4 v[148:149], v[144:147], off offset:256
	s_cbranch_execz .LBB0_146

; #define PG8_BAR __builtin_amdgcn_s_barrier()
;     DI bool zero_after(const Unit& u) const { return (u.pn >> 2) == 2; }
; template <class Epi, class Sched, bool ALIGN_EPI = false, bool SP2 = false>
; __device__ __forceinline__ void gemm_phase(PG8_LAS unsigned char* lds, const Gemm g, const Sched& S, const Epi& E, const int tid) {
;     ...
;         if (!has_next) break;
;         if (E.zero_after(cur)) {
; #pragma unroll
;         for (int a = 0; a < 2; ++a)
; #pragma unroll
;             for (int b = 0; b < 2; ++b)
; #pragma unroll
;                 for (int m = 0; m < 4; ++m)
; #pragma unroll
;                     for (int n = 0; n < 2; ++n) acc[a][b][m][n] = (f32x4){zz, zz, zz, zz};
;         }
;         cur = nxt; cA = nA; cB = nB; ++ui;
;         if constexpr (ALIGN_EPI) { if (wr == 1) PG8_BAR; }
;     }
.LBB0_146:
	s_waitcnt vmcnt(0)
	v_lshlrev_b32_e32 v146, 16, v133
	v_and_b32_e32 v147, 0xffff0000, v133
	v_lshlrev_b32_e32 v133, 16, v134
	v_lshlrev_b32_e32 v144, 16, v132
	v_and_b32_e32 v145, 0xffff0000, v132
	v_max_f32_e32 v133, 0x1e3ce508, v133
	v_and_b32_e32 v148, 0xffff0000, v134
	v_max_f32_e32 v132, v144, v144
	v_rcp_f32_e32 v134, v133
	v_max_f32_e32 v133, v145, v145
	v_max_f32_e32 v132, 0x1e3ce508, v132
	v_max_f32_e32 v133, 0x1e3ce508, v133
	v_max_f32_e32 v144, 0x1e3ce508, v146
	v_max_f32_e32 v145, 0x1e3ce508, v147
	v_rcp_f32_e32 v132, v132
	v_rcp_f32_e32 v133, v133
	v_rcp_f32_e32 v144, v144
	v_rcp_f32_e32 v145, v145
	v_lshlrev_b32_e32 v149, 16, v135
	v_and_b32_e32 v150, 0xffff0000, v135
	v_pk_mul_f32 v[132:133], v[140:141], v[132:133]
	v_pk_mul_f32 v[140:141], v[142:143], v[144:145]
	v_max_f32_e32 v135, 0x1e3ce508, v148
	v_max_f32_e32 v146, 0x1e3ce508, v149
	v_max_f32_e32 v142, 0x1e3ce508, v150
	v_rcp_f32_e32 v135, v135
	v_rcp_f32_e32 v146, v146
	v_rcp_f32_e32 v147, v142
	v_pk_mul_f32 v[8:9], v[8:9], v[132:133]
	v_pk_mul_f32 v[132:133], v[136:137], v[134:135]
	v_pk_mul_f32 v[10:11], v[10:11], v[140:141]
	v_pk_mul_f32 v[134:135], v[138:139], v[146:147]
	v_pk_mul_f32 v[4:5], v[4:5], v[132:133]
	v_pk_mul_f32 v[6:7], v[6:7], v[134:135]
	s_andn2_b64 vcc, exec, s[38:39]
	s_mov_b64 s[6:7], -1
	s_cbranch_vccnz .LBB0_43
